# lever 2/7.3: phase 1 (rmsnorm+modulate) hand-written with 8 columns per lane so that H and the bf16 residual copy are stored with 16-byte stores (was 8-byte), next rows' loads in flight
# speedup vs baseline: 1.0029x; 1.0029x over previous
.LBB0_121:
	s_cmp_lt_i32 s40, 2
	s_cselect_b64 s[10:11], -1, 0
	s_and_b64 s[0:1], s[0:1], s[10:11]
	s_andn2_b64 vcc, exec, s[0:1]
	s_cbranch_vccnz .LBB0_133
	v_mov_b32_e32 v9, 0
	global_load_dwordx2 v[160:161], v9, s[96:97] sc0
	global_load_dwordx2 v[162:163], v9, s[96:97] offset:8 sc0
	global_load_dwordx2 v[164:165], v9, s[96:97] offset:64 sc0
	v_mbcnt_lo_u32_b32 v0, -1, 0
	v_mbcnt_hi_u32_b32 v0, -1, v0
	v_lshlrev_b32_e32 v1, 5, v0
	v_lshlrev_b32_e32 v8, 4, v0
	v_xor_b32_e32 v2, 1, v0
	v_lshlrev_b32_e32 v2, 2, v2
	v_xor_b32_e32 v3, 2, v0
	v_lshlrev_b32_e32 v3, 2, v3
	v_xor_b32_e32 v4, 4, v0
	v_lshlrev_b32_e32 v4, 2, v4
	v_xor_b32_e32 v5, 8, v0
	v_lshlrev_b32_e32 v5, 2, v5
	v_xor_b32_e32 v6, 16, v0
	v_lshlrev_b32_e32 v6, 2, v6
	v_xor_b32_e32 v7, 32, v0
	v_lshlrev_b32_e32 v7, 2, v7
	s_waitcnt vmcnt(0)
	v_readfirstlane_b32 s24, v160
	v_readfirstlane_b32 s25, v161
	v_readfirstlane_b32 s26, v162
	v_readfirstlane_b32 s27, v163
	v_readfirstlane_b32 s28, v164
	v_readfirstlane_b32 s29, v165
	s_nop 4
	global_load_dwordx4 v[10:13], v1, s[28:29]
	global_load_dwordx4 v[14:17], v1, s[28:29] offset:16
	global_load_dwordx4 v[18:21], v1, s[28:29] offset:2048
	global_load_dwordx4 v[22:25], v1, s[28:29] offset:2064
	s_mov_b32 s9, s8
	s_lshl_b32 s9, s9, 12
	s_add_u32 s12, s24, s9
	s_addc_u32 s13, s25, 0
	s_add_i32 s9, s8, 0x800
	s_lshl_b32 s9, s9, 12
	s_add_u32 s14, s24, s9
	s_addc_u32 s15, s25, 0
	global_load_dwordx4 v[32:35], v1, s[12:13]
	global_load_dwordx4 v[36:39], v1, s[12:13] offset:16
	global_load_dwordx4 v[40:43], v1, s[12:13] offset:2048
	global_load_dwordx4 v[44:47], v1, s[12:13] offset:2064
	global_load_dwordx4 v[48:51], v1, s[14:15]
	global_load_dwordx4 v[52:55], v1, s[14:15] offset:16
	global_load_dwordx4 v[56:59], v1, s[14:15] offset:2048
	global_load_dwordx4 v[60:63], v1, s[14:15] offset:2064
	s_add_u32 s16, s54, 0x18000
	s_addc_u32 s17, s55, 0
	global_load_dwordx4 v[128:131], v1, s[16:17]
	global_load_dwordx4 v[132:135], v1, s[16:17] offset:16
	global_load_dwordx4 v[136:139], v1, s[16:17] offset:2048
	global_load_dwordx4 v[140:143], v1, s[16:17] offset:2064
	s_add_u32 s16, s16, 0x1000
	s_addc_u32 s17, s17, 0
	global_load_dwordx4 v[96:99], v1, s[16:17]
	global_load_dwordx4 v[100:103], v1, s[16:17] offset:16
	global_load_dwordx4 v[104:107], v1, s[16:17] offset:2048
	global_load_dwordx4 v[108:111], v1, s[16:17] offset:2064
	s_add_u32 s16, s54, 0x18000
	s_addc_u32 s17, s55, 0
	global_load_dwordx4 v[144:147], v1, s[16:17]
	global_load_dwordx4 v[148:151], v1, s[16:17] offset:16
	global_load_dwordx4 v[152:155], v1, s[16:17] offset:2048
	global_load_dwordx4 v[156:159], v1, s[16:17] offset:2064
	s_add_u32 s16, s16, 0x1000
	s_addc_u32 s17, s17, 0
	global_load_dwordx4 v[112:115], v1, s[16:17]
	global_load_dwordx4 v[116:119], v1, s[16:17] offset:16
	global_load_dwordx4 v[120:123], v1, s[16:17] offset:2048
	global_load_dwordx4 v[124:127], v1, s[16:17] offset:2064
	s_mov_b32 s9, s8
	s_lshl_b32 s9, s9, 12
	s_add_u32 s12, s26, s9
	s_addc_u32 s13, s27, 0
	s_add_i32 s9, s8, 0x800
	s_lshl_b32 s9, s9, 12
	s_add_u32 s14, s26, s9
	s_addc_u32 s15, s27, 0
	global_load_dwordx4 v[64:67], v1, s[12:13]
	global_load_dwordx4 v[68:71], v1, s[12:13] offset:16
	global_load_dwordx4 v[72:75], v1, s[12:13] offset:2048
	global_load_dwordx4 v[76:79], v1, s[12:13] offset:2064
	global_load_dwordx4 v[80:83], v1, s[14:15]
	global_load_dwordx4 v[84:87], v1, s[14:15] offset:16
	global_load_dwordx4 v[88:91], v1, s[14:15] offset:2048
	global_load_dwordx4 v[92:95], v1, s[14:15] offset:2064
	s_waitcnt vmcnt(24)
	v_mul_f32_e32 v166, v32, v32
	v_fmac_f32_e32 v166, v33, v33
	v_mul_f32_e32 v167, v34, v34
	v_fmac_f32_e32 v167, v35, v35
	v_add_f32_e32 v160, v166, v167
	v_mul_f32_e32 v166, v36, v36
	v_fmac_f32_e32 v166, v37, v37
	v_mul_f32_e32 v167, v38, v38
	v_fmac_f32_e32 v167, v39, v39
	v_add_f32_e32 v166, v166, v167
	v_add_f32_e32 v160, v160, v166
	v_mul_f32_e32 v166, v40, v40
	v_fmac_f32_e32 v166, v41, v41
	v_mul_f32_e32 v167, v42, v42
	v_fmac_f32_e32 v167, v43, v43
	v_add_f32_e32 v166, v166, v167
	v_add_f32_e32 v160, v160, v166
	v_mul_f32_e32 v166, v44, v44
	v_fmac_f32_e32 v166, v45, v45
	v_mul_f32_e32 v167, v46, v46
	v_fmac_f32_e32 v167, v47, v47
	v_add_f32_e32 v166, v166, v167
	v_add_f32_e32 v160, v160, v166
	v_mul_f32_e32 v166, v48, v48
	v_fmac_f32_e32 v166, v49, v49
	v_mul_f32_e32 v167, v50, v50
	v_fmac_f32_e32 v167, v51, v51
	v_add_f32_e32 v161, v166, v167
	v_mul_f32_e32 v166, v52, v52
	v_fmac_f32_e32 v166, v53, v53
	v_mul_f32_e32 v167, v54, v54
	v_fmac_f32_e32 v167, v55, v55
	v_add_f32_e32 v166, v166, v167
	v_add_f32_e32 v161, v161, v166
	v_mul_f32_e32 v166, v56, v56
	v_fmac_f32_e32 v166, v57, v57
	v_mul_f32_e32 v167, v58, v58
	v_fmac_f32_e32 v167, v59, v59
	v_add_f32_e32 v166, v166, v167
	v_add_f32_e32 v161, v161, v166
	v_mul_f32_e32 v166, v60, v60
	v_fmac_f32_e32 v166, v61, v61
	v_mul_f32_e32 v167, v62, v62
	v_fmac_f32_e32 v167, v63, v63
	v_add_f32_e32 v166, v166, v167
	v_add_f32_e32 v161, v161, v166
	ds_bpermute_b32 v164, v2, v160
	ds_bpermute_b32 v165, v2, v161
	s_waitcnt lgkmcnt(0)
	v_add_f32_e32 v160, v160, v164
	v_add_f32_e32 v161, v161, v165
	ds_bpermute_b32 v164, v3, v160
	ds_bpermute_b32 v165, v3, v161
	s_waitcnt lgkmcnt(0)
	v_add_f32_e32 v160, v160, v164
	v_add_f32_e32 v161, v161, v165
	ds_bpermute_b32 v164, v4, v160
	ds_bpermute_b32 v165, v4, v161
	s_waitcnt lgkmcnt(0)
	v_add_f32_e32 v160, v160, v164
	v_add_f32_e32 v161, v161, v165
	ds_bpermute_b32 v164, v5, v160
	ds_bpermute_b32 v165, v5, v161
	s_waitcnt lgkmcnt(0)
	v_add_f32_e32 v160, v160, v164
	v_add_f32_e32 v161, v161, v165
	ds_bpermute_b32 v164, v6, v160
	ds_bpermute_b32 v165, v6, v161
	s_waitcnt lgkmcnt(0)
	v_add_f32_e32 v160, v160, v164
	v_add_f32_e32 v161, v161, v165
	ds_bpermute_b32 v164, v7, v160
	ds_bpermute_b32 v165, v7, v161
	s_waitcnt lgkmcnt(0)
	v_add_f32_e32 v160, v160, v164
	v_add_f32_e32 v161, v161, v165
	v_mul_f32_e32 v162, 0x3a800000, v160
	v_add_f32_e32 v162, 0x358637bd, v162
	v_mul_f32_e32 v163, 0x3a800000, v161
	v_add_f32_e32 v163, 0x358637bd, v163
	v_rsq_f32_e32 v162, v162
	v_rsq_f32_e32 v163, v163
	s_waitcnt vmcnt(8)
	s_mov_b32 s9, s8
	s_lshl_b32 s9, s9, 11
	s_add_u32 s0, s54, s9
	s_addc_u32 s1, s55, 0
	s_add_u32 s4, s0, 0xda00000
	s_addc_u32 s5, s1, 0
	s_add_u32 s0, s0, 0x4200000
	s_addc_u32 s1, s1, 0
	v_mul_f32_e32 v168, v32, v162
	v_mul_f32_e32 v168, v168, v10
	v_add_f32_e32 v172, 1.0, v96
	v_fma_f32 v168, v168, v172, v128
	v_mul_f32_e32 v169, v33, v162
	v_mul_f32_e32 v169, v169, v11
	v_add_f32_e32 v173, 1.0, v97
	v_fma_f32 v169, v169, v173, v129
	v_mul_f32_e32 v170, v34, v162
	v_mul_f32_e32 v170, v170, v12
	v_add_f32_e32 v174, 1.0, v98
	v_fma_f32 v170, v170, v174, v130
	v_mul_f32_e32 v171, v35, v162
	v_mul_f32_e32 v171, v171, v13
	v_add_f32_e32 v175, 1.0, v99
	v_fma_f32 v171, v171, v175, v131
	v_cvt_pk_bf16_f32 v176, v168, v169
	v_cvt_pk_bf16_f32 v177, v170, v171
	v_cvt_pk_bf16_f32 v180, v32, v33
	v_cvt_pk_bf16_f32 v181, v34, v35
	v_mul_f32_e32 v168, v36, v162
	v_mul_f32_e32 v168, v168, v14
	v_add_f32_e32 v172, 1.0, v100
	v_fma_f32 v168, v168, v172, v132
	v_mul_f32_e32 v169, v37, v162
	v_mul_f32_e32 v169, v169, v15
	v_add_f32_e32 v173, 1.0, v101
	v_fma_f32 v169, v169, v173, v133
	v_mul_f32_e32 v170, v38, v162
	v_mul_f32_e32 v170, v170, v16
	v_add_f32_e32 v174, 1.0, v102
	v_fma_f32 v170, v170, v174, v134
	v_mul_f32_e32 v171, v39, v162
	v_mul_f32_e32 v171, v171, v17
	v_add_f32_e32 v175, 1.0, v103
	v_fma_f32 v171, v171, v175, v135
	v_cvt_pk_bf16_f32 v178, v168, v169
	v_cvt_pk_bf16_f32 v179, v170, v171
	v_cvt_pk_bf16_f32 v182, v36, v37
	v_cvt_pk_bf16_f32 v183, v38, v39
	global_store_dwordx4 v8, v[176:179], s[0:1]
	global_store_dwordx4 v8, v[180:183], s[4:5]
	v_mul_f32_e32 v168, v40, v162
	v_mul_f32_e32 v168, v168, v18
	v_add_f32_e32 v172, 1.0, v104
	v_fma_f32 v168, v168, v172, v136
	v_mul_f32_e32 v169, v41, v162
	v_mul_f32_e32 v169, v169, v19
	v_add_f32_e32 v173, 1.0, v105
	v_fma_f32 v169, v169, v173, v137
	v_mul_f32_e32 v170, v42, v162
	v_mul_f32_e32 v170, v170, v20
	v_add_f32_e32 v174, 1.0, v106
	v_fma_f32 v170, v170, v174, v138
	v_mul_f32_e32 v171, v43, v162
	v_mul_f32_e32 v171, v171, v21
	v_add_f32_e32 v175, 1.0, v107
	v_fma_f32 v171, v171, v175, v139
	v_cvt_pk_bf16_f32 v184, v168, v169
	v_cvt_pk_bf16_f32 v185, v170, v171
	v_cvt_pk_bf16_f32 v188, v40, v41
	v_cvt_pk_bf16_f32 v189, v42, v43
	v_mul_f32_e32 v168, v44, v162
	v_mul_f32_e32 v168, v168, v22
	v_add_f32_e32 v172, 1.0, v108
	v_fma_f32 v168, v168, v172, v140
	v_mul_f32_e32 v169, v45, v162
	v_mul_f32_e32 v169, v169, v23
	v_add_f32_e32 v173, 1.0, v109
	v_fma_f32 v169, v169, v173, v141
	v_mul_f32_e32 v170, v46, v162
	v_mul_f32_e32 v170, v170, v24
	v_add_f32_e32 v174, 1.0, v110
	v_fma_f32 v170, v170, v174, v142
	v_mul_f32_e32 v171, v47, v162
	v_mul_f32_e32 v171, v171, v25
	v_add_f32_e32 v175, 1.0, v111
	v_fma_f32 v171, v171, v175, v143
	v_cvt_pk_bf16_f32 v186, v168, v169
	v_cvt_pk_bf16_f32 v187, v170, v171
	v_cvt_pk_bf16_f32 v190, v44, v45
	v_cvt_pk_bf16_f32 v191, v46, v47
	global_store_dwordx4 v8, v[184:187], s[0:1] offset:1024
	global_store_dwordx4 v8, v[188:191], s[4:5] offset:1024
	s_add_i32 s9, s8, 0x800
	s_lshl_b32 s9, s9, 11
	s_add_u32 s0, s54, s9
	s_addc_u32 s1, s55, 0
	s_add_u32 s4, s0, 0xda00000
	s_addc_u32 s5, s1, 0
	s_add_u32 s0, s0, 0x4200000
	s_addc_u32 s1, s1, 0
	v_mul_f32_e32 v168, v48, v163
	v_mul_f32_e32 v168, v168, v10
	v_add_f32_e32 v172, 1.0, v112
	v_fma_f32 v168, v168, v172, v144
	v_mul_f32_e32 v169, v49, v163
	v_mul_f32_e32 v169, v169, v11
	v_add_f32_e32 v173, 1.0, v113
	v_fma_f32 v169, v169, v173, v145
	v_mul_f32_e32 v170, v50, v163
	v_mul_f32_e32 v170, v170, v12
	v_add_f32_e32 v174, 1.0, v114
	v_fma_f32 v170, v170, v174, v146
	v_mul_f32_e32 v171, v51, v163
	v_mul_f32_e32 v171, v171, v13
	v_add_f32_e32 v175, 1.0, v115
	v_fma_f32 v171, v171, v175, v147
	v_cvt_pk_bf16_f32 v176, v168, v169
	v_cvt_pk_bf16_f32 v177, v170, v171
	v_cvt_pk_bf16_f32 v180, v48, v49
	v_cvt_pk_bf16_f32 v181, v50, v51
	v_mul_f32_e32 v168, v52, v163
	v_mul_f32_e32 v168, v168, v14
	v_add_f32_e32 v172, 1.0, v116
	v_fma_f32 v168, v168, v172, v148
	v_mul_f32_e32 v169, v53, v163
	v_mul_f32_e32 v169, v169, v15
	v_add_f32_e32 v173, 1.0, v117
	v_fma_f32 v169, v169, v173, v149
	v_mul_f32_e32 v170, v54, v163
	v_mul_f32_e32 v170, v170, v16
	v_add_f32_e32 v174, 1.0, v118
	v_fma_f32 v170, v170, v174, v150
	v_mul_f32_e32 v171, v55, v163
	v_mul_f32_e32 v171, v171, v17
	v_add_f32_e32 v175, 1.0, v119
	v_fma_f32 v171, v171, v175, v151
	v_cvt_pk_bf16_f32 v178, v168, v169
	v_cvt_pk_bf16_f32 v179, v170, v171
	v_cvt_pk_bf16_f32 v182, v52, v53
	v_cvt_pk_bf16_f32 v183, v54, v55
	global_store_dwordx4 v8, v[176:179], s[0:1]
	global_store_dwordx4 v8, v[180:183], s[4:5]
	v_mul_f32_e32 v168, v56, v163
	v_mul_f32_e32 v168, v168, v18
	v_add_f32_e32 v172, 1.0, v120
	v_fma_f32 v168, v168, v172, v152
	v_mul_f32_e32 v169, v57, v163
	v_mul_f32_e32 v169, v169, v19
	v_add_f32_e32 v173, 1.0, v121
	v_fma_f32 v169, v169, v173, v153
	v_mul_f32_e32 v170, v58, v163
	v_mul_f32_e32 v170, v170, v20
	v_add_f32_e32 v174, 1.0, v122
	v_fma_f32 v170, v170, v174, v154
	v_mul_f32_e32 v171, v59, v163
	v_mul_f32_e32 v171, v171, v21
	v_add_f32_e32 v175, 1.0, v123
	v_fma_f32 v171, v171, v175, v155
	v_cvt_pk_bf16_f32 v184, v168, v169
	v_cvt_pk_bf16_f32 v185, v170, v171
	v_cvt_pk_bf16_f32 v188, v56, v57
	v_cvt_pk_bf16_f32 v189, v58, v59
	v_mul_f32_e32 v168, v60, v163
	v_mul_f32_e32 v168, v168, v22
	v_add_f32_e32 v172, 1.0, v124
	v_fma_f32 v168, v168, v172, v156
	v_mul_f32_e32 v169, v61, v163
	v_mul_f32_e32 v169, v169, v23
	v_add_f32_e32 v173, 1.0, v125
	v_fma_f32 v169, v169, v173, v157
	v_mul_f32_e32 v170, v62, v163
	v_mul_f32_e32 v170, v170, v24
	v_add_f32_e32 v174, 1.0, v126
	v_fma_f32 v170, v170, v174, v158
	v_mul_f32_e32 v171, v63, v163
	v_mul_f32_e32 v171, v171, v25
	v_add_f32_e32 v175, 1.0, v127
	v_fma_f32 v171, v171, v175, v159
	v_cvt_pk_bf16_f32 v186, v168, v169
	v_cvt_pk_bf16_f32 v187, v170, v171
	v_cvt_pk_bf16_f32 v190, v60, v61
	v_cvt_pk_bf16_f32 v191, v62, v63
	global_store_dwordx4 v8, v[184:187], s[0:1] offset:1024
	global_store_dwordx4 v8, v[188:191], s[4:5] offset:1024
	s_add_u32 s16, s54, 0x0
	s_addc_u32 s17, s55, 0
	global_load_dwordx4 v[128:131], v1, s[16:17]
	global_load_dwordx4 v[132:135], v1, s[16:17] offset:16
	global_load_dwordx4 v[136:139], v1, s[16:17] offset:2048
	global_load_dwordx4 v[140:143], v1, s[16:17] offset:2064
	s_add_u32 s16, s16, 0x1000
	s_addc_u32 s17, s17, 0
	global_load_dwordx4 v[96:99], v1, s[16:17]
	global_load_dwordx4 v[100:103], v1, s[16:17] offset:16
	global_load_dwordx4 v[104:107], v1, s[16:17] offset:2048
	global_load_dwordx4 v[108:111], v1, s[16:17] offset:2064
	s_add_u32 s16, s54, 0x6000
	s_addc_u32 s17, s55, 0
	global_load_dwordx4 v[144:147], v1, s[16:17]
	global_load_dwordx4 v[148:151], v1, s[16:17] offset:16
	global_load_dwordx4 v[152:155], v1, s[16:17] offset:2048
	global_load_dwordx4 v[156:159], v1, s[16:17] offset:2064
	s_add_u32 s16, s16, 0x1000
	s_addc_u32 s17, s17, 0
	global_load_dwordx4 v[112:115], v1, s[16:17]
	global_load_dwordx4 v[116:119], v1, s[16:17] offset:16
	global_load_dwordx4 v[120:123], v1, s[16:17] offset:2048
	global_load_dwordx4 v[124:127], v1, s[16:17] offset:2064
	s_add_i32 s9, s8, 0x1000
	s_lshl_b32 s9, s9, 12
	s_add_u32 s12, s26, s9
	s_addc_u32 s13, s27, 0
	s_add_i32 s9, s8, 0x1800
	s_lshl_b32 s9, s9, 12
	s_add_u32 s14, s26, s9
	s_addc_u32 s15, s27, 0
	global_load_dwordx4 v[32:35], v1, s[12:13]
	global_load_dwordx4 v[36:39], v1, s[12:13] offset:16
	global_load_dwordx4 v[40:43], v1, s[12:13] offset:2048
	global_load_dwordx4 v[44:47], v1, s[12:13] offset:2064
	global_load_dwordx4 v[48:51], v1, s[14:15]
	global_load_dwordx4 v[52:55], v1, s[14:15] offset:16
	global_load_dwordx4 v[56:59], v1, s[14:15] offset:2048
	global_load_dwordx4 v[60:63], v1, s[14:15] offset:2064
	s_waitcnt vmcnt(32)
	v_mul_f32_e32 v166, v64, v64
	v_fmac_f32_e32 v166, v65, v65
	v_mul_f32_e32 v167, v66, v66
	v_fmac_f32_e32 v167, v67, v67
	v_add_f32_e32 v160, v166, v167
	v_mul_f32_e32 v166, v68, v68
	v_fmac_f32_e32 v166, v69, v69
	v_mul_f32_e32 v167, v70, v70
	v_fmac_f32_e32 v167, v71, v71
	v_add_f32_e32 v166, v166, v167
	v_add_f32_e32 v160, v160, v166
	v_mul_f32_e32 v166, v72, v72
	v_fmac_f32_e32 v166, v73, v73
	v_mul_f32_e32 v167, v74, v74
	v_fmac_f32_e32 v167, v75, v75
	v_add_f32_e32 v166, v166, v167
	v_add_f32_e32 v160, v160, v166
	v_mul_f32_e32 v166, v76, v76
	v_fmac_f32_e32 v166, v77, v77
	v_mul_f32_e32 v167, v78, v78
	v_fmac_f32_e32 v167, v79, v79
	v_add_f32_e32 v166, v166, v167
	v_add_f32_e32 v160, v160, v166
	v_mul_f32_e32 v166, v80, v80
	v_fmac_f32_e32 v166, v81, v81
	v_mul_f32_e32 v167, v82, v82
	v_fmac_f32_e32 v167, v83, v83
	v_add_f32_e32 v161, v166, v167
	v_mul_f32_e32 v166, v84, v84
	v_fmac_f32_e32 v166, v85, v85
	v_mul_f32_e32 v167, v86, v86
	v_fmac_f32_e32 v167, v87, v87
	v_add_f32_e32 v166, v166, v167
	v_add_f32_e32 v161, v161, v166
	v_mul_f32_e32 v166, v88, v88
	v_fmac_f32_e32 v166, v89, v89
	v_mul_f32_e32 v167, v90, v90
	v_fmac_f32_e32 v167, v91, v91
	v_add_f32_e32 v166, v166, v167
	v_add_f32_e32 v161, v161, v166
	v_mul_f32_e32 v166, v92, v92
	v_fmac_f32_e32 v166, v93, v93
	v_mul_f32_e32 v167, v94, v94
	v_fmac_f32_e32 v167, v95, v95
	v_add_f32_e32 v166, v166, v167
	v_add_f32_e32 v161, v161, v166
	ds_bpermute_b32 v164, v2, v160
	ds_bpermute_b32 v165, v2, v161
	s_waitcnt lgkmcnt(0)
	v_add_f32_e32 v160, v160, v164
	v_add_f32_e32 v161, v161, v165
	ds_bpermute_b32 v164, v3, v160
	ds_bpermute_b32 v165, v3, v161
	s_waitcnt lgkmcnt(0)
	v_add_f32_e32 v160, v160, v164
	v_add_f32_e32 v161, v161, v165
	ds_bpermute_b32 v164, v4, v160
	ds_bpermute_b32 v165, v4, v161
	s_waitcnt lgkmcnt(0)
	v_add_f32_e32 v160, v160, v164
	v_add_f32_e32 v161, v161, v165
	ds_bpermute_b32 v164, v5, v160
	ds_bpermute_b32 v165, v5, v161
	s_waitcnt lgkmcnt(0)
	v_add_f32_e32 v160, v160, v164
	v_add_f32_e32 v161, v161, v165
	ds_bpermute_b32 v164, v6, v160
	ds_bpermute_b32 v165, v6, v161
	s_waitcnt lgkmcnt(0)
	v_add_f32_e32 v160, v160, v164
	v_add_f32_e32 v161, v161, v165
	ds_bpermute_b32 v164, v7, v160
	ds_bpermute_b32 v165, v7, v161
	s_waitcnt lgkmcnt(0)
	v_add_f32_e32 v160, v160, v164
	v_add_f32_e32 v161, v161, v165
	v_mul_f32_e32 v162, 0x3a800000, v160
	v_add_f32_e32 v162, 0x358637bd, v162
	v_mul_f32_e32 v163, 0x3a800000, v161
	v_add_f32_e32 v163, 0x358637bd, v163
	v_rsq_f32_e32 v162, v162
	v_rsq_f32_e32 v163, v163
	s_waitcnt vmcnt(8)
	s_add_i32 s9, s8, 0x1000
	s_lshl_b32 s9, s9, 11
	s_add_u32 s0, s54, s9
	s_addc_u32 s1, s55, 0
	s_add_u32 s4, s0, 0xda00000
	s_addc_u32 s5, s1, 0
	s_add_u32 s0, s0, 0x4200000
	s_addc_u32 s1, s1, 0
	v_mul_f32_e32 v168, v64, v162
	v_mul_f32_e32 v168, v168, v10
	v_add_f32_e32 v172, 1.0, v96
	v_fma_f32 v168, v168, v172, v128
	v_mul_f32_e32 v169, v65, v162
	v_mul_f32_e32 v169, v169, v11
	v_add_f32_e32 v173, 1.0, v97
	v_fma_f32 v169, v169, v173, v129
	v_mul_f32_e32 v170, v66, v162
	v_mul_f32_e32 v170, v170, v12
	v_add_f32_e32 v174, 1.0, v98
	v_fma_f32 v170, v170, v174, v130
	v_mul_f32_e32 v171, v67, v162
	v_mul_f32_e32 v171, v171, v13
	v_add_f32_e32 v175, 1.0, v99
	v_fma_f32 v171, v171, v175, v131
	v_cvt_pk_bf16_f32 v176, v168, v169
	v_cvt_pk_bf16_f32 v177, v170, v171
	v_cvt_pk_bf16_f32 v180, v64, v65
	v_cvt_pk_bf16_f32 v181, v66, v67
	v_mul_f32_e32 v168, v68, v162
	v_mul_f32_e32 v168, v168, v14
	v_add_f32_e32 v172, 1.0, v100
	v_fma_f32 v168, v168, v172, v132
	v_mul_f32_e32 v169, v69, v162
	v_mul_f32_e32 v169, v169, v15
	v_add_f32_e32 v173, 1.0, v101
	v_fma_f32 v169, v169, v173, v133
	v_mul_f32_e32 v170, v70, v162
	v_mul_f32_e32 v170, v170, v16
	v_add_f32_e32 v174, 1.0, v102
	v_fma_f32 v170, v170, v174, v134
	v_mul_f32_e32 v171, v71, v162
	v_mul_f32_e32 v171, v171, v17
	v_add_f32_e32 v175, 1.0, v103
	v_fma_f32 v171, v171, v175, v135
	v_cvt_pk_bf16_f32 v178, v168, v169
	v_cvt_pk_bf16_f32 v179, v170, v171
	v_cvt_pk_bf16_f32 v182, v68, v69
	v_cvt_pk_bf16_f32 v183, v70, v71
	global_store_dwordx4 v8, v[176:179], s[0:1]
	global_store_dwordx4 v8, v[180:183], s[4:5]
	v_mul_f32_e32 v168, v72, v162
	v_mul_f32_e32 v168, v168, v18
	v_add_f32_e32 v172, 1.0, v104
	v_fma_f32 v168, v168, v172, v136
	v_mul_f32_e32 v169, v73, v162
	v_mul_f32_e32 v169, v169, v19
	v_add_f32_e32 v173, 1.0, v105
	v_fma_f32 v169, v169, v173, v137
	v_mul_f32_e32 v170, v74, v162
	v_mul_f32_e32 v170, v170, v20
	v_add_f32_e32 v174, 1.0, v106
	v_fma_f32 v170, v170, v174, v138
	v_mul_f32_e32 v171, v75, v162
	v_mul_f32_e32 v171, v171, v21
	v_add_f32_e32 v175, 1.0, v107
	v_fma_f32 v171, v171, v175, v139
	v_cvt_pk_bf16_f32 v184, v168, v169
	v_cvt_pk_bf16_f32 v185, v170, v171
	v_cvt_pk_bf16_f32 v188, v72, v73
	v_cvt_pk_bf16_f32 v189, v74, v75
	v_mul_f32_e32 v168, v76, v162
	v_mul_f32_e32 v168, v168, v22
	v_add_f32_e32 v172, 1.0, v108
	v_fma_f32 v168, v168, v172, v140
	v_mul_f32_e32 v169, v77, v162
	v_mul_f32_e32 v169, v169, v23
	v_add_f32_e32 v173, 1.0, v109
	v_fma_f32 v169, v169, v173, v141
	v_mul_f32_e32 v170, v78, v162
	v_mul_f32_e32 v170, v170, v24
	v_add_f32_e32 v174, 1.0, v110
	v_fma_f32 v170, v170, v174, v142
	v_mul_f32_e32 v171, v79, v162
	v_mul_f32_e32 v171, v171, v25
	v_add_f32_e32 v175, 1.0, v111
	v_fma_f32 v171, v171, v175, v143
	v_cvt_pk_bf16_f32 v186, v168, v169
	v_cvt_pk_bf16_f32 v187, v170, v171
	v_cvt_pk_bf16_f32 v190, v76, v77
	v_cvt_pk_bf16_f32 v191, v78, v79
	global_store_dwordx4 v8, v[184:187], s[0:1] offset:1024
	global_store_dwordx4 v8, v[188:191], s[4:5] offset:1024
	s_add_i32 s9, s8, 0x1800
	s_lshl_b32 s9, s9, 11
	s_add_u32 s0, s54, s9
	s_addc_u32 s1, s55, 0
	s_add_u32 s4, s0, 0xda00000
	s_addc_u32 s5, s1, 0
	s_add_u32 s0, s0, 0x4200000
	s_addc_u32 s1, s1, 0
	v_mul_f32_e32 v168, v80, v163
	v_mul_f32_e32 v168, v168, v10
	v_add_f32_e32 v172, 1.0, v112
	v_fma_f32 v168, v168, v172, v144
	v_mul_f32_e32 v169, v81, v163
	v_mul_f32_e32 v169, v169, v11
	v_add_f32_e32 v173, 1.0, v113
	v_fma_f32 v169, v169, v173, v145
	v_mul_f32_e32 v170, v82, v163
	v_mul_f32_e32 v170, v170, v12
	v_add_f32_e32 v174, 1.0, v114
	v_fma_f32 v170, v170, v174, v146
	v_mul_f32_e32 v171, v83, v163
	v_mul_f32_e32 v171, v171, v13
	v_add_f32_e32 v175, 1.0, v115
	v_fma_f32 v171, v171, v175, v147
	v_cvt_pk_bf16_f32 v176, v168, v169
	v_cvt_pk_bf16_f32 v177, v170, v171
	v_cvt_pk_bf16_f32 v180, v80, v81
	v_cvt_pk_bf16_f32 v181, v82, v83
	v_mul_f32_e32 v168, v84, v163
	v_mul_f32_e32 v168, v168, v14
	v_add_f32_e32 v172, 1.0, v116
	v_fma_f32 v168, v168, v172, v148
	v_mul_f32_e32 v169, v85, v163
	v_mul_f32_e32 v169, v169, v15
	v_add_f32_e32 v173, 1.0, v117
	v_fma_f32 v169, v169, v173, v149
	v_mul_f32_e32 v170, v86, v163
	v_mul_f32_e32 v170, v170, v16
	v_add_f32_e32 v174, 1.0, v118
	v_fma_f32 v170, v170, v174, v150
	v_mul_f32_e32 v171, v87, v163
	v_mul_f32_e32 v171, v171, v17
	v_add_f32_e32 v175, 1.0, v119
	v_fma_f32 v171, v171, v175, v151
	v_cvt_pk_bf16_f32 v178, v168, v169
	v_cvt_pk_bf16_f32 v179, v170, v171
	v_cvt_pk_bf16_f32 v182, v84, v85
	v_cvt_pk_bf16_f32 v183, v86, v87
	global_store_dwordx4 v8, v[176:179], s[0:1]
	global_store_dwordx4 v8, v[180:183], s[4:5]
	v_mul_f32_e32 v168, v88, v163
	v_mul_f32_e32 v168, v168, v18
	v_add_f32_e32 v172, 1.0, v120
	v_fma_f32 v168, v168, v172, v152
	v_mul_f32_e32 v169, v89, v163
	v_mul_f32_e32 v169, v169, v19
	v_add_f32_e32 v173, 1.0, v121
	v_fma_f32 v169, v169, v173, v153
	v_mul_f32_e32 v170, v90, v163
	v_mul_f32_e32 v170, v170, v20
	v_add_f32_e32 v174, 1.0, v122
	v_fma_f32 v170, v170, v174, v154
	v_mul_f32_e32 v171, v91, v163
	v_mul_f32_e32 v171, v171, v21
	v_add_f32_e32 v175, 1.0, v123
	v_fma_f32 v171, v171, v175, v155
	v_cvt_pk_bf16_f32 v184, v168, v169
	v_cvt_pk_bf16_f32 v185, v170, v171
	v_cvt_pk_bf16_f32 v188, v88, v89
	v_cvt_pk_bf16_f32 v189, v90, v91
	v_mul_f32_e32 v168, v92, v163
	v_mul_f32_e32 v168, v168, v22
	v_add_f32_e32 v172, 1.0, v124
	v_fma_f32 v168, v168, v172, v156
	v_mul_f32_e32 v169, v93, v163
	v_mul_f32_e32 v169, v169, v23
	v_add_f32_e32 v173, 1.0, v125
	v_fma_f32 v169, v169, v173, v157
	v_mul_f32_e32 v170, v94, v163
	v_mul_f32_e32 v170, v170, v24
	v_add_f32_e32 v174, 1.0, v126
	v_fma_f32 v170, v170, v174, v158
	v_mul_f32_e32 v171, v95, v163
	v_mul_f32_e32 v171, v171, v25
	v_add_f32_e32 v175, 1.0, v127
	v_fma_f32 v171, v171, v175, v159
	v_cvt_pk_bf16_f32 v186, v168, v169
	v_cvt_pk_bf16_f32 v187, v170, v171
	v_cvt_pk_bf16_f32 v190, v92, v93
	v_cvt_pk_bf16_f32 v191, v94, v95
	global_store_dwordx4 v8, v[184:187], s[0:1] offset:1024
	global_store_dwordx4 v8, v[188:191], s[4:5] offset:1024
	s_add_u32 s16, s54, 0xc000
	s_addc_u32 s17, s55, 0
	global_load_dwordx4 v[128:131], v1, s[16:17]
	global_load_dwordx4 v[132:135], v1, s[16:17] offset:16
	global_load_dwordx4 v[136:139], v1, s[16:17] offset:2048
	global_load_dwordx4 v[140:143], v1, s[16:17] offset:2064
	s_add_u32 s16, s16, 0x1000
	s_addc_u32 s17, s17, 0
	global_load_dwordx4 v[96:99], v1, s[16:17]
	global_load_dwordx4 v[100:103], v1, s[16:17] offset:16
	global_load_dwordx4 v[104:107], v1, s[16:17] offset:2048
	global_load_dwordx4 v[108:111], v1, s[16:17] offset:2064
	s_add_u32 s16, s54, 0x12000
	s_addc_u32 s17, s55, 0
	global_load_dwordx4 v[144:147], v1, s[16:17]
	global_load_dwordx4 v[148:151], v1, s[16:17] offset:16
	global_load_dwordx4 v[152:155], v1, s[16:17] offset:2048
	global_load_dwordx4 v[156:159], v1, s[16:17] offset:2064
	s_add_u32 s16, s16, 0x1000
	s_addc_u32 s17, s17, 0
	global_load_dwordx4 v[112:115], v1, s[16:17]
	global_load_dwordx4 v[116:119], v1, s[16:17] offset:16
	global_load_dwordx4 v[120:123], v1, s[16:17] offset:2048
	global_load_dwordx4 v[124:127], v1, s[16:17] offset:2064
	s_waitcnt vmcnt(24)
	v_mul_f32_e32 v166, v32, v32
	v_fmac_f32_e32 v166, v33, v33
	v_mul_f32_e32 v167, v34, v34
	v_fmac_f32_e32 v167, v35, v35
	v_add_f32_e32 v160, v166, v167
	v_mul_f32_e32 v166, v36, v36
	v_fmac_f32_e32 v166, v37, v37
	v_mul_f32_e32 v167, v38, v38
	v_fmac_f32_e32 v167, v39, v39
	v_add_f32_e32 v166, v166, v167
	v_add_f32_e32 v160, v160, v166
	v_mul_f32_e32 v166, v40, v40
	v_fmac_f32_e32 v166, v41, v41
	v_mul_f32_e32 v167, v42, v42
	v_fmac_f32_e32 v167, v43, v43
	v_add_f32_e32 v166, v166, v167
	v_add_f32_e32 v160, v160, v166
	v_mul_f32_e32 v166, v44, v44
	v_fmac_f32_e32 v166, v45, v45
	v_mul_f32_e32 v167, v46, v46
	v_fmac_f32_e32 v167, v47, v47
	v_add_f32_e32 v166, v166, v167
	v_add_f32_e32 v160, v160, v166
	v_mul_f32_e32 v166, v48, v48
	v_fmac_f32_e32 v166, v49, v49
	v_mul_f32_e32 v167, v50, v50
	v_fmac_f32_e32 v167, v51, v51
	v_add_f32_e32 v161, v166, v167
	v_mul_f32_e32 v166, v52, v52
	v_fmac_f32_e32 v166, v53, v53
	v_mul_f32_e32 v167, v54, v54
	v_fmac_f32_e32 v167, v55, v55
	v_add_f32_e32 v166, v166, v167
	v_add_f32_e32 v161, v161, v166
	v_mul_f32_e32 v166, v56, v56
	v_fmac_f32_e32 v166, v57, v57
	v_mul_f32_e32 v167, v58, v58
	v_fmac_f32_e32 v167, v59, v59
	v_add_f32_e32 v166, v166, v167
	v_add_f32_e32 v161, v161, v166
	v_mul_f32_e32 v166, v60, v60
	v_fmac_f32_e32 v166, v61, v61
	v_mul_f32_e32 v167, v62, v62
	v_fmac_f32_e32 v167, v63, v63
	v_add_f32_e32 v166, v166, v167
	v_add_f32_e32 v161, v161, v166
	ds_bpermute_b32 v164, v2, v160
	ds_bpermute_b32 v165, v2, v161
	s_waitcnt lgkmcnt(0)
	v_add_f32_e32 v160, v160, v164
	v_add_f32_e32 v161, v161, v165
	ds_bpermute_b32 v164, v3, v160
	ds_bpermute_b32 v165, v3, v161
	s_waitcnt lgkmcnt(0)
	v_add_f32_e32 v160, v160, v164
	v_add_f32_e32 v161, v161, v165
	ds_bpermute_b32 v164, v4, v160
	ds_bpermute_b32 v165, v4, v161
	s_waitcnt lgkmcnt(0)
	v_add_f32_e32 v160, v160, v164
	v_add_f32_e32 v161, v161, v165
	ds_bpermute_b32 v164, v5, v160
	ds_bpermute_b32 v165, v5, v161
	s_waitcnt lgkmcnt(0)
	v_add_f32_e32 v160, v160, v164
	v_add_f32_e32 v161, v161, v165
	ds_bpermute_b32 v164, v6, v160
	ds_bpermute_b32 v165, v6, v161
	s_waitcnt lgkmcnt(0)
	v_add_f32_e32 v160, v160, v164
	v_add_f32_e32 v161, v161, v165
	ds_bpermute_b32 v164, v7, v160
	ds_bpermute_b32 v165, v7, v161
	s_waitcnt lgkmcnt(0)
	v_add_f32_e32 v160, v160, v164
	v_add_f32_e32 v161, v161, v165
	v_mul_f32_e32 v162, 0x3a800000, v160
	v_add_f32_e32 v162, 0x358637bd, v162
	v_mul_f32_e32 v163, 0x3a800000, v161
	v_add_f32_e32 v163, 0x358637bd, v163
	v_rsq_f32_e32 v162, v162
	v_rsq_f32_e32 v163, v163
	s_waitcnt vmcnt(0)
	s_add_i32 s9, s8, 0x2000
	s_lshl_b32 s9, s9, 11
	s_add_u32 s0, s54, s9
	s_addc_u32 s1, s55, 0
	s_add_u32 s4, s0, 0xda00000
	s_addc_u32 s5, s1, 0
	s_add_u32 s0, s0, 0x4200000
	s_addc_u32 s1, s1, 0
	v_mul_f32_e32 v168, v32, v162
	v_mul_f32_e32 v168, v168, v10
	v_add_f32_e32 v172, 1.0, v96
	v_fma_f32 v168, v168, v172, v128
	v_mul_f32_e32 v169, v33, v162
	v_mul_f32_e32 v169, v169, v11
	v_add_f32_e32 v173, 1.0, v97
	v_fma_f32 v169, v169, v173, v129
	v_mul_f32_e32 v170, v34, v162
	v_mul_f32_e32 v170, v170, v12
	v_add_f32_e32 v174, 1.0, v98
	v_fma_f32 v170, v170, v174, v130
	v_mul_f32_e32 v171, v35, v162
	v_mul_f32_e32 v171, v171, v13
	v_add_f32_e32 v175, 1.0, v99
	v_fma_f32 v171, v171, v175, v131
	v_cvt_pk_bf16_f32 v176, v168, v169
	v_cvt_pk_bf16_f32 v177, v170, v171
	v_cvt_pk_bf16_f32 v180, v32, v33
	v_cvt_pk_bf16_f32 v181, v34, v35
	v_mul_f32_e32 v168, v36, v162
	v_mul_f32_e32 v168, v168, v14
	v_add_f32_e32 v172, 1.0, v100
	v_fma_f32 v168, v168, v172, v132
	v_mul_f32_e32 v169, v37, v162
	v_mul_f32_e32 v169, v169, v15
	v_add_f32_e32 v173, 1.0, v101
	v_fma_f32 v169, v169, v173, v133
	v_mul_f32_e32 v170, v38, v162
	v_mul_f32_e32 v170, v170, v16
	v_add_f32_e32 v174, 1.0, v102
	v_fma_f32 v170, v170, v174, v134
	v_mul_f32_e32 v171, v39, v162
	v_mul_f32_e32 v171, v171, v17
	v_add_f32_e32 v175, 1.0, v103
	v_fma_f32 v171, v171, v175, v135
	v_cvt_pk_bf16_f32 v178, v168, v169
	v_cvt_pk_bf16_f32 v179, v170, v171
	v_cvt_pk_bf16_f32 v182, v36, v37
	v_cvt_pk_bf16_f32 v183, v38, v39
	global_store_dwordx4 v8, v[176:179], s[0:1]
	global_store_dwordx4 v8, v[180:183], s[4:5]
	v_mul_f32_e32 v168, v40, v162
	v_mul_f32_e32 v168, v168, v18
	v_add_f32_e32 v172, 1.0, v104
	v_fma_f32 v168, v168, v172, v136
	v_mul_f32_e32 v169, v41, v162
	v_mul_f32_e32 v169, v169, v19
	v_add_f32_e32 v173, 1.0, v105
	v_fma_f32 v169, v169, v173, v137
	v_mul_f32_e32 v170, v42, v162
	v_mul_f32_e32 v170, v170, v20
	v_add_f32_e32 v174, 1.0, v106
	v_fma_f32 v170, v170, v174, v138
	v_mul_f32_e32 v171, v43, v162
	v_mul_f32_e32 v171, v171, v21
	v_add_f32_e32 v175, 1.0, v107
	v_fma_f32 v171, v171, v175, v139
	v_cvt_pk_bf16_f32 v184, v168, v169
	v_cvt_pk_bf16_f32 v185, v170, v171
	v_cvt_pk_bf16_f32 v188, v40, v41
	v_cvt_pk_bf16_f32 v189, v42, v43
	v_mul_f32_e32 v168, v44, v162
	v_mul_f32_e32 v168, v168, v22
	v_add_f32_e32 v172, 1.0, v108
	v_fma_f32 v168, v168, v172, v140
	v_mul_f32_e32 v169, v45, v162
	v_mul_f32_e32 v169, v169, v23
	v_add_f32_e32 v173, 1.0, v109
	v_fma_f32 v169, v169, v173, v141
	v_mul_f32_e32 v170, v46, v162
	v_mul_f32_e32 v170, v170, v24
	v_add_f32_e32 v174, 1.0, v110
	v_fma_f32 v170, v170, v174, v142
	v_mul_f32_e32 v171, v47, v162
	v_mul_f32_e32 v171, v171, v25
	v_add_f32_e32 v175, 1.0, v111
	v_fma_f32 v171, v171, v175, v143
	v_cvt_pk_bf16_f32 v186, v168, v169
	v_cvt_pk_bf16_f32 v187, v170, v171
	v_cvt_pk_bf16_f32 v190, v44, v45
	v_cvt_pk_bf16_f32 v191, v46, v47
	global_store_dwordx4 v8, v[184:187], s[0:1] offset:1024
	global_store_dwordx4 v8, v[188:191], s[4:5] offset:1024
	s_add_i32 s9, s8, 0x2800
	s_lshl_b32 s9, s9, 11
	s_add_u32 s0, s54, s9
	s_addc_u32 s1, s55, 0
	s_add_u32 s4, s0, 0xda00000
	s_addc_u32 s5, s1, 0
	s_add_u32 s0, s0, 0x4200000
	s_addc_u32 s1, s1, 0
	v_mul_f32_e32 v168, v48, v163
	v_mul_f32_e32 v168, v168, v10
	v_add_f32_e32 v172, 1.0, v112
	v_fma_f32 v168, v168, v172, v144
	v_mul_f32_e32 v169, v49, v163
	v_mul_f32_e32 v169, v169, v11
	v_add_f32_e32 v173, 1.0, v113
	v_fma_f32 v169, v169, v173, v145
	v_mul_f32_e32 v170, v50, v163
	v_mul_f32_e32 v170, v170, v12
	v_add_f32_e32 v174, 1.0, v114
	v_fma_f32 v170, v170, v174, v146
	v_mul_f32_e32 v171, v51, v163
	v_mul_f32_e32 v171, v171, v13
	v_add_f32_e32 v175, 1.0, v115
	v_fma_f32 v171, v171, v175, v147
	v_cvt_pk_bf16_f32 v176, v168, v169
	v_cvt_pk_bf16_f32 v177, v170, v171
	v_cvt_pk_bf16_f32 v180, v48, v49
	v_cvt_pk_bf16_f32 v181, v50, v51
	v_mul_f32_e32 v168, v52, v163
	v_mul_f32_e32 v168, v168, v14
	v_add_f32_e32 v172, 1.0, v116
	v_fma_f32 v168, v168, v172, v148
	v_mul_f32_e32 v169, v53, v163
	v_mul_f32_e32 v169, v169, v15
	v_add_f32_e32 v173, 1.0, v117
	v_fma_f32 v169, v169, v173, v149
	v_mul_f32_e32 v170, v54, v163
	v_mul_f32_e32 v170, v170, v16
	v_add_f32_e32 v174, 1.0, v118
	v_fma_f32 v170, v170, v174, v150
	v_mul_f32_e32 v171, v55, v163
	v_mul_f32_e32 v171, v171, v17
	v_add_f32_e32 v175, 1.0, v119
	v_fma_f32 v171, v171, v175, v151
	v_cvt_pk_bf16_f32 v178, v168, v169
	v_cvt_pk_bf16_f32 v179, v170, v171
	v_cvt_pk_bf16_f32 v182, v52, v53
	v_cvt_pk_bf16_f32 v183, v54, v55
	global_store_dwordx4 v8, v[176:179], s[0:1]
	global_store_dwordx4 v8, v[180:183], s[4:5]
	v_mul_f32_e32 v168, v56, v163
	v_mul_f32_e32 v168, v168, v18
	v_add_f32_e32 v172, 1.0, v120
	v_fma_f32 v168, v168, v172, v152
	v_mul_f32_e32 v169, v57, v163
	v_mul_f32_e32 v169, v169, v19
	v_add_f32_e32 v173, 1.0, v121
	v_fma_f32 v169, v169, v173, v153
	v_mul_f32_e32 v170, v58, v163
	v_mul_f32_e32 v170, v170, v20
	v_add_f32_e32 v174, 1.0, v122
	v_fma_f32 v170, v170, v174, v154
	v_mul_f32_e32 v171, v59, v163
	v_mul_f32_e32 v171, v171, v21
	v_add_f32_e32 v175, 1.0, v123
	v_fma_f32 v171, v171, v175, v155
	v_cvt_pk_bf16_f32 v184, v168, v169
	v_cvt_pk_bf16_f32 v185, v170, v171
	v_cvt_pk_bf16_f32 v188, v56, v57
	v_cvt_pk_bf16_f32 v189, v58, v59
	v_mul_f32_e32 v168, v60, v163
	v_mul_f32_e32 v168, v168, v22
	v_add_f32_e32 v172, 1.0, v124
	v_fma_f32 v168, v168, v172, v156
	v_mul_f32_e32 v169, v61, v163
	v_mul_f32_e32 v169, v169, v23
	v_add_f32_e32 v173, 1.0, v125
	v_fma_f32 v169, v169, v173, v157
	v_mul_f32_e32 v170, v62, v163
	v_mul_f32_e32 v170, v170, v24
	v_add_f32_e32 v174, 1.0, v126
	v_fma_f32 v170, v170, v174, v158
	v_mul_f32_e32 v171, v63, v163
	v_mul_f32_e32 v171, v171, v25
	v_add_f32_e32 v175, 1.0, v127
	v_fma_f32 v171, v171, v175, v159
	v_cvt_pk_bf16_f32 v186, v168, v169
	v_cvt_pk_bf16_f32 v187, v170, v171
	v_cvt_pk_bf16_f32 v190, v60, v61
	v_cvt_pk_bf16_f32 v191, v62, v63
	global_store_dwordx4 v8, v[184:187], s[0:1] offset:1024
	global_store_dwordx4 v8, v[188:191], s[4:5] offset:1024
